# s_setprio 1 around GEMM k-loop MFMA blocks (compute wave prioritized over loader wave)
# speedup vs baseline: 1.0183x; 1.0183x over previous
.LBB0_114:
	s_andn2_saveexec_b64 s[48:49], s[48:49]
	s_cbranch_execz .LBB0_116
	s_and_b32 s40, s72, 0x10000
	v_add_u32_e32 v0, s40, v192
	v_or_b32_e32 v2, s40, v193
	v_add_u32_e32 v14, v0, v194
	v_add_u32_e32 v15, v0, v195
	v_add_u32_e32 v199, v0, v196
	v_add_u32_e32 v0, v0, v197
	v_add_u32_e32 v205, v2, v194
	v_add_u32_e32 v228, v2, v195
	v_add_u32_e32 v250, v2, v196
	v_add_u32_e32 v251, v2, v197
	s_setprio 1
	ds_read_b128 v[2:5], v14 offset:0
	ds_read_b128 v[6:9], v14 offset:4096
	ds_read_b128 v[10:13], v14 offset:8192
	ds_read_b128 v[208:211], v14 offset:12288
	ds_read_b128 v[242:245], v205 offset:0
	ds_read_b128 v[246:249], v205 offset:4096
	ds_read_b128 v[214:217], v15 offset:0
	ds_read_b128 v[230:233], v15 offset:4096
	ds_read_b128 v[234:237], v15 offset:8192
	ds_read_b128 v[238:241], v15 offset:12288
	s_waitcnt lgkmcnt(4)
	v_mfma_f32_32x32x16_bf16 v[128:143], v[2:5], v[242:245], v[128:143]
	v_mfma_f32_32x32x16_bf16 v[96:111], v[6:9], v[242:245], v[96:111]
	v_mfma_f32_32x32x16_bf16 v[64:79], v[10:13], v[242:245], v[64:79]
	v_mfma_f32_32x32x16_bf16 v[32:47], v[208:211], v[242:245], v[32:47]
	ds_read_b128 v[242:245], v228 offset:0
	v_mfma_f32_32x32x16_bf16 v[112:127], v[2:5], v[246:249], v[112:127]
	v_mfma_f32_32x32x16_bf16 v[80:95], v[6:9], v[246:249], v[80:95]
	v_mfma_f32_32x32x16_bf16 v[48:63], v[10:13], v[246:249], v[48:63]
	v_mfma_f32_32x32x16_bf16 v[16:31], v[208:211], v[246:249], v[16:31]
	ds_read_b128 v[246:249], v228 offset:4096
	ds_read_b128 v[2:5], v199 offset:0
	ds_read_b128 v[6:9], v199 offset:4096
	ds_read_b128 v[10:13], v199 offset:8192
	ds_read_b128 v[208:211], v199 offset:12288
	s_waitcnt lgkmcnt(5)
	v_mfma_f32_32x32x16_bf16 v[128:143], v[214:217], v[242:245], v[128:143]
	v_mfma_f32_32x32x16_bf16 v[96:111], v[230:233], v[242:245], v[96:111]
	v_mfma_f32_32x32x16_bf16 v[64:79], v[234:237], v[242:245], v[64:79]
	v_mfma_f32_32x32x16_bf16 v[32:47], v[238:241], v[242:245], v[32:47]
	ds_read_b128 v[242:245], v250 offset:0
	s_waitcnt lgkmcnt(5)
	v_mfma_f32_32x32x16_bf16 v[112:127], v[214:217], v[246:249], v[112:127]
	v_mfma_f32_32x32x16_bf16 v[80:95], v[230:233], v[246:249], v[80:95]
	v_mfma_f32_32x32x16_bf16 v[48:63], v[234:237], v[246:249], v[48:63]
	v_mfma_f32_32x32x16_bf16 v[16:31], v[238:241], v[246:249], v[16:31]
	ds_read_b128 v[246:249], v250 offset:4096
	ds_read_b128 v[214:217], v0 offset:0
	ds_read_b128 v[230:233], v0 offset:4096
	ds_read_b128 v[234:237], v0 offset:8192
	ds_read_b128 v[238:241], v0 offset:12288
	s_waitcnt lgkmcnt(5)
	v_mfma_f32_32x32x16_bf16 v[128:143], v[2:5], v[242:245], v[128:143]
	v_mfma_f32_32x32x16_bf16 v[96:111], v[6:9], v[242:245], v[96:111]
	v_mfma_f32_32x32x16_bf16 v[64:79], v[10:13], v[242:245], v[64:79]
	v_mfma_f32_32x32x16_bf16 v[32:47], v[208:211], v[242:245], v[32:47]
	ds_read_b128 v[242:245], v251 offset:0
	s_waitcnt lgkmcnt(5)
	v_mfma_f32_32x32x16_bf16 v[112:127], v[2:5], v[246:249], v[112:127]
	v_mfma_f32_32x32x16_bf16 v[80:95], v[6:9], v[246:249], v[80:95]
	v_mfma_f32_32x32x16_bf16 v[48:63], v[10:13], v[246:249], v[48:63]
	v_mfma_f32_32x32x16_bf16 v[16:31], v[208:211], v[246:249], v[16:31]
	ds_read_b128 v[246:249], v251 offset:4096
	s_waitcnt lgkmcnt(1)
	v_mfma_f32_32x32x16_bf16 v[128:143], v[214:217], v[242:245], v[128:143]
	v_mfma_f32_32x32x16_bf16 v[96:111], v[230:233], v[242:245], v[96:111]
	v_mfma_f32_32x32x16_bf16 v[64:79], v[234:237], v[242:245], v[64:79]
	v_mfma_f32_32x32x16_bf16 v[32:47], v[238:241], v[242:245], v[32:47]
	s_waitcnt lgkmcnt(0)
	v_mfma_f32_32x32x16_bf16 v[112:127], v[214:217], v[246:249], v[112:127]
	v_mfma_f32_32x32x16_bf16 v[80:95], v[230:233], v[246:249], v[80:95]
	v_mfma_f32_32x32x16_bf16 v[48:63], v[234:237], v[246:249], v[48:63]
	v_mfma_f32_32x32x16_bf16 v[16:31], v[238:241], v[246:249], v[16:31]
	s_nop 15
	s_nop 7

	s_setprio 0

.LBB0_121:
	s_andn2_saveexec_b64 s[48:49], s[48:49]
	s_cbranch_execz .LBB0_108
	s_and_b32 s40, s72, 0x10000
	v_add_u32_e32 v0, s40, v192
	v_or_b32_e32 v2, s40, v193
	v_add_u32_e32 v14, v0, v194
	v_add_u32_e32 v15, v0, v195
	v_add_u32_e32 v199, v0, v196
	v_add_u32_e32 v0, v0, v197
	v_add_u32_e32 v205, v2, v194
	v_add_u32_e32 v228, v2, v195
	v_add_u32_e32 v250, v2, v196
	v_add_u32_e32 v251, v2, v197
	s_setprio 1
	ds_read_b128 v[2:5], v14 offset:0
	ds_read_b128 v[6:9], v14 offset:4096
	ds_read_b128 v[10:13], v14 offset:8192
	ds_read_b128 v[208:211], v14 offset:12288
	ds_read_b128 v[242:245], v205 offset:0
	ds_read_b128 v[246:249], v205 offset:4096
	ds_read_b128 v[214:217], v15 offset:0
	ds_read_b128 v[230:233], v15 offset:4096
	ds_read_b128 v[234:237], v15 offset:8192
	ds_read_b128 v[238:241], v15 offset:12288
	s_waitcnt lgkmcnt(4)
	v_mfma_f32_32x32x16_bf16 v[128:143], v[2:5], v[242:245], v[128:143]
	v_mfma_f32_32x32x16_bf16 v[96:111], v[6:9], v[242:245], v[96:111]
	v_mfma_f32_32x32x16_bf16 v[64:79], v[10:13], v[242:245], v[64:79]
	v_mfma_f32_32x32x16_bf16 v[32:47], v[208:211], v[242:245], v[32:47]
	ds_read_b128 v[242:245], v228 offset:0
	v_mfma_f32_32x32x16_bf16 v[112:127], v[2:5], v[246:249], v[112:127]
	v_mfma_f32_32x32x16_bf16 v[80:95], v[6:9], v[246:249], v[80:95]
	v_mfma_f32_32x32x16_bf16 v[48:63], v[10:13], v[246:249], v[48:63]
	v_mfma_f32_32x32x16_bf16 v[16:31], v[208:211], v[246:249], v[16:31]
	ds_read_b128 v[246:249], v228 offset:4096
	ds_read_b128 v[2:5], v199 offset:0
	ds_read_b128 v[6:9], v199 offset:4096
	ds_read_b128 v[10:13], v199 offset:8192
	ds_read_b128 v[208:211], v199 offset:12288
	s_waitcnt lgkmcnt(5)
	v_mfma_f32_32x32x16_bf16 v[128:143], v[214:217], v[242:245], v[128:143]
	v_mfma_f32_32x32x16_bf16 v[96:111], v[230:233], v[242:245], v[96:111]
	v_mfma_f32_32x32x16_bf16 v[64:79], v[234:237], v[242:245], v[64:79]
	v_mfma_f32_32x32x16_bf16 v[32:47], v[238:241], v[242:245], v[32:47]
	ds_read_b128 v[242:245], v250 offset:0
	s_waitcnt lgkmcnt(5)
	v_mfma_f32_32x32x16_bf16 v[112:127], v[214:217], v[246:249], v[112:127]
	v_mfma_f32_32x32x16_bf16 v[80:95], v[230:233], v[246:249], v[80:95]
	v_mfma_f32_32x32x16_bf16 v[48:63], v[234:237], v[246:249], v[48:63]
	v_mfma_f32_32x32x16_bf16 v[16:31], v[238:241], v[246:249], v[16:31]
	ds_read_b128 v[246:249], v250 offset:4096
	ds_read_b128 v[214:217], v0 offset:0
	ds_read_b128 v[230:233], v0 offset:4096
	ds_read_b128 v[234:237], v0 offset:8192
	ds_read_b128 v[238:241], v0 offset:12288
	s_waitcnt lgkmcnt(5)
	v_mfma_f32_32x32x16_bf16 v[128:143], v[2:5], v[242:245], v[128:143]
	v_mfma_f32_32x32x16_bf16 v[96:111], v[6:9], v[242:245], v[96:111]
	v_mfma_f32_32x32x16_bf16 v[64:79], v[10:13], v[242:245], v[64:79]
	v_mfma_f32_32x32x16_bf16 v[32:47], v[208:211], v[242:245], v[32:47]
	ds_read_b128 v[242:245], v251 offset:0
	s_waitcnt lgkmcnt(5)
	v_mfma_f32_32x32x16_bf16 v[112:127], v[2:5], v[246:249], v[112:127]
	v_mfma_f32_32x32x16_bf16 v[80:95], v[6:9], v[246:249], v[80:95]
	v_mfma_f32_32x32x16_bf16 v[48:63], v[10:13], v[246:249], v[48:63]
	v_mfma_f32_32x32x16_bf16 v[16:31], v[208:211], v[246:249], v[16:31]
	ds_read_b128 v[246:249], v251 offset:4096
	s_waitcnt lgkmcnt(1)
	v_mfma_f32_32x32x16_bf16 v[128:143], v[214:217], v[242:245], v[128:143]
	v_mfma_f32_32x32x16_bf16 v[96:111], v[230:233], v[242:245], v[96:111]
	v_mfma_f32_32x32x16_bf16 v[64:79], v[234:237], v[242:245], v[64:79]
	v_mfma_f32_32x32x16_bf16 v[32:47], v[238:241], v[242:245], v[32:47]
	s_waitcnt lgkmcnt(0)
	v_mfma_f32_32x32x16_bf16 v[112:127], v[214:217], v[246:249], v[112:127]
	v_mfma_f32_32x32x16_bf16 v[80:95], v[230:233], v[246:249], v[80:95]
	v_mfma_f32_32x32x16_bf16 v[48:63], v[234:237], v[246:249], v[48:63]
	v_mfma_f32_32x32x16_bf16 v[16:31], v[238:241], v[246:249], v[16:31]
	s_nop 15
	s_nop 7

	s_setprio 0
	s_branch .LBB0_108

.LBB0_352:
	s_andn2_saveexec_b64 s[48:49], s[48:49]
	s_cbranch_execz .LBB0_354
	s_and_b32 s40, s29, 0x10000
	v_add_u32_e32 v0, s40, v198
	v_or_b32_e32 v2, s40, v199
	v_add_u32_e32 v14, v0, v201
	v_add_u32_e32 v15, v0, v202
	v_add_u32_e32 v205, v0, v203
	v_add_u32_e32 v0, v0, v204
	v_add_u32_e32 v248, v2, v201
	v_add_u32_e32 v249, v2, v202
	v_add_u32_e32 v250, v2, v203
	v_add_u32_e32 v251, v2, v204
	s_setprio 1
	ds_read_b128 v[2:5], v14 offset:0
	ds_read_b128 v[6:9], v14 offset:4096
	ds_read_b128 v[10:13], v14 offset:8192
	ds_read_b128 v[208:211], v14 offset:12288
	ds_read_b128 v[240:243], v248 offset:0
	ds_read_b128 v[244:247], v248 offset:4096
	ds_read_b128 v[214:217], v15 offset:0
	ds_read_b128 v[228:231], v15 offset:4096
	ds_read_b128 v[232:235], v15 offset:8192
	ds_read_b128 v[236:239], v15 offset:12288
	s_waitcnt lgkmcnt(4)
	v_mfma_f32_32x32x16_bf16 v[128:143], v[2:5], v[240:243], v[128:143]
	v_mfma_f32_32x32x16_bf16 v[96:111], v[6:9], v[240:243], v[96:111]
	v_mfma_f32_32x32x16_bf16 v[64:79], v[10:13], v[240:243], v[64:79]
	v_mfma_f32_32x32x16_bf16 v[32:47], v[208:211], v[240:243], v[32:47]
	ds_read_b128 v[240:243], v249 offset:0
	v_mfma_f32_32x32x16_bf16 v[112:127], v[2:5], v[244:247], v[112:127]
	v_mfma_f32_32x32x16_bf16 v[80:95], v[6:9], v[244:247], v[80:95]
	v_mfma_f32_32x32x16_bf16 v[48:63], v[10:13], v[244:247], v[48:63]
	v_mfma_f32_32x32x16_bf16 v[16:31], v[208:211], v[244:247], v[16:31]
	ds_read_b128 v[244:247], v249 offset:4096
	ds_read_b128 v[2:5], v205 offset:0
	ds_read_b128 v[6:9], v205 offset:4096
	ds_read_b128 v[10:13], v205 offset:8192
	ds_read_b128 v[208:211], v205 offset:12288
	s_waitcnt lgkmcnt(5)
	v_mfma_f32_32x32x16_bf16 v[128:143], v[214:217], v[240:243], v[128:143]
	v_mfma_f32_32x32x16_bf16 v[96:111], v[228:231], v[240:243], v[96:111]
	v_mfma_f32_32x32x16_bf16 v[64:79], v[232:235], v[240:243], v[64:79]
	v_mfma_f32_32x32x16_bf16 v[32:47], v[236:239], v[240:243], v[32:47]
	ds_read_b128 v[240:243], v250 offset:0
	s_waitcnt lgkmcnt(5)
	v_mfma_f32_32x32x16_bf16 v[112:127], v[214:217], v[244:247], v[112:127]
	v_mfma_f32_32x32x16_bf16 v[80:95], v[228:231], v[244:247], v[80:95]
	v_mfma_f32_32x32x16_bf16 v[48:63], v[232:235], v[244:247], v[48:63]
	v_mfma_f32_32x32x16_bf16 v[16:31], v[236:239], v[244:247], v[16:31]
	ds_read_b128 v[244:247], v250 offset:4096
	ds_read_b128 v[214:217], v0 offset:0
	ds_read_b128 v[228:231], v0 offset:4096
	ds_read_b128 v[232:235], v0 offset:8192
	ds_read_b128 v[236:239], v0 offset:12288
	s_waitcnt lgkmcnt(5)
	v_mfma_f32_32x32x16_bf16 v[128:143], v[2:5], v[240:243], v[128:143]
	v_mfma_f32_32x32x16_bf16 v[96:111], v[6:9], v[240:243], v[96:111]
	v_mfma_f32_32x32x16_bf16 v[64:79], v[10:13], v[240:243], v[64:79]
	v_mfma_f32_32x32x16_bf16 v[32:47], v[208:211], v[240:243], v[32:47]
	ds_read_b128 v[240:243], v251 offset:0
	s_waitcnt lgkmcnt(5)
	v_mfma_f32_32x32x16_bf16 v[112:127], v[2:5], v[244:247], v[112:127]
	v_mfma_f32_32x32x16_bf16 v[80:95], v[6:9], v[244:247], v[80:95]
	v_mfma_f32_32x32x16_bf16 v[48:63], v[10:13], v[244:247], v[48:63]
	v_mfma_f32_32x32x16_bf16 v[16:31], v[208:211], v[244:247], v[16:31]
	ds_read_b128 v[244:247], v251 offset:4096
	s_waitcnt lgkmcnt(1)
	v_mfma_f32_32x32x16_bf16 v[128:143], v[214:217], v[240:243], v[128:143]
	v_mfma_f32_32x32x16_bf16 v[96:111], v[228:231], v[240:243], v[96:111]
	v_mfma_f32_32x32x16_bf16 v[64:79], v[232:235], v[240:243], v[64:79]
	v_mfma_f32_32x32x16_bf16 v[32:47], v[236:239], v[240:243], v[32:47]
	s_waitcnt lgkmcnt(0)
	v_mfma_f32_32x32x16_bf16 v[112:127], v[214:217], v[244:247], v[112:127]
	v_mfma_f32_32x32x16_bf16 v[80:95], v[228:231], v[244:247], v[80:95]
	v_mfma_f32_32x32x16_bf16 v[48:63], v[232:235], v[244:247], v[48:63]
	v_mfma_f32_32x32x16_bf16 v[16:31], v[236:239], v[244:247], v[16:31]
	s_nop 15
	s_nop 7

	s_setprio 0

.LBB0_367:
	s_andn2_saveexec_b64 s[48:49], s[48:49]
	s_cbranch_execz .LBB0_338
	s_and_b32 s40, s29, 0x10000
	v_add_u32_e32 v0, s40, v198
	v_or_b32_e32 v2, s40, v199
	v_add_u32_e32 v14, v0, v201
	v_add_u32_e32 v15, v0, v202
	v_add_u32_e32 v205, v0, v203
	v_add_u32_e32 v0, v0, v204
	v_add_u32_e32 v248, v2, v201
	v_add_u32_e32 v249, v2, v202
	v_add_u32_e32 v250, v2, v203
	v_add_u32_e32 v251, v2, v204
	s_setprio 1
	ds_read_b128 v[2:5], v14 offset:0
	ds_read_b128 v[6:9], v14 offset:4096
	ds_read_b128 v[10:13], v14 offset:8192
	ds_read_b128 v[208:211], v14 offset:12288
	ds_read_b128 v[240:243], v248 offset:0
	ds_read_b128 v[244:247], v248 offset:4096
	ds_read_b128 v[214:217], v15 offset:0
	ds_read_b128 v[228:231], v15 offset:4096
	ds_read_b128 v[232:235], v15 offset:8192
	ds_read_b128 v[236:239], v15 offset:12288
	s_waitcnt lgkmcnt(4)
	v_mfma_f32_32x32x16_bf16 v[128:143], v[2:5], v[240:243], v[128:143]
	v_mfma_f32_32x32x16_bf16 v[96:111], v[6:9], v[240:243], v[96:111]
	v_mfma_f32_32x32x16_bf16 v[64:79], v[10:13], v[240:243], v[64:79]
	v_mfma_f32_32x32x16_bf16 v[32:47], v[208:211], v[240:243], v[32:47]
	ds_read_b128 v[240:243], v249 offset:0
	v_mfma_f32_32x32x16_bf16 v[112:127], v[2:5], v[244:247], v[112:127]
	v_mfma_f32_32x32x16_bf16 v[80:95], v[6:9], v[244:247], v[80:95]
	v_mfma_f32_32x32x16_bf16 v[48:63], v[10:13], v[244:247], v[48:63]
	v_mfma_f32_32x32x16_bf16 v[16:31], v[208:211], v[244:247], v[16:31]
	ds_read_b128 v[244:247], v249 offset:4096
	ds_read_b128 v[2:5], v205 offset:0
	ds_read_b128 v[6:9], v205 offset:4096
	ds_read_b128 v[10:13], v205 offset:8192
	ds_read_b128 v[208:211], v205 offset:12288
	s_waitcnt lgkmcnt(5)
	v_mfma_f32_32x32x16_bf16 v[128:143], v[214:217], v[240:243], v[128:143]
	v_mfma_f32_32x32x16_bf16 v[96:111], v[228:231], v[240:243], v[96:111]
	v_mfma_f32_32x32x16_bf16 v[64:79], v[232:235], v[240:243], v[64:79]
	v_mfma_f32_32x32x16_bf16 v[32:47], v[236:239], v[240:243], v[32:47]
	ds_read_b128 v[240:243], v250 offset:0
	s_waitcnt lgkmcnt(5)
	v_mfma_f32_32x32x16_bf16 v[112:127], v[214:217], v[244:247], v[112:127]
	v_mfma_f32_32x32x16_bf16 v[80:95], v[228:231], v[244:247], v[80:95]
	v_mfma_f32_32x32x16_bf16 v[48:63], v[232:235], v[244:247], v[48:63]
	v_mfma_f32_32x32x16_bf16 v[16:31], v[236:239], v[244:247], v[16:31]
	ds_read_b128 v[244:247], v250 offset:4096
	ds_read_b128 v[214:217], v0 offset:0
	ds_read_b128 v[228:231], v0 offset:4096
	ds_read_b128 v[232:235], v0 offset:8192
	ds_read_b128 v[236:239], v0 offset:12288
	s_waitcnt lgkmcnt(5)
	v_mfma_f32_32x32x16_bf16 v[128:143], v[2:5], v[240:243], v[128:143]
	v_mfma_f32_32x32x16_bf16 v[96:111], v[6:9], v[240:243], v[96:111]
	v_mfma_f32_32x32x16_bf16 v[64:79], v[10:13], v[240:243], v[64:79]
	v_mfma_f32_32x32x16_bf16 v[32:47], v[208:211], v[240:243], v[32:47]
	ds_read_b128 v[240:243], v251 offset:0
	s_waitcnt lgkmcnt(5)
	v_mfma_f32_32x32x16_bf16 v[112:127], v[2:5], v[244:247], v[112:127]
	v_mfma_f32_32x32x16_bf16 v[80:95], v[6:9], v[244:247], v[80:95]
	v_mfma_f32_32x32x16_bf16 v[48:63], v[10:13], v[244:247], v[48:63]
	v_mfma_f32_32x32x16_bf16 v[16:31], v[208:211], v[244:247], v[16:31]
	ds_read_b128 v[244:247], v251 offset:4096
	s_waitcnt lgkmcnt(1)
	v_mfma_f32_32x32x16_bf16 v[128:143], v[214:217], v[240:243], v[128:143]
	v_mfma_f32_32x32x16_bf16 v[96:111], v[228:231], v[240:243], v[96:111]
	v_mfma_f32_32x32x16_bf16 v[64:79], v[232:235], v[240:243], v[64:79]
	v_mfma_f32_32x32x16_bf16 v[32:47], v[236:239], v[240:243], v[32:47]
	s_waitcnt lgkmcnt(0)
	v_mfma_f32_32x32x16_bf16 v[112:127], v[214:217], v[244:247], v[112:127]
	v_mfma_f32_32x32x16_bf16 v[80:95], v[228:231], v[244:247], v[80:95]
	v_mfma_f32_32x32x16_bf16 v[48:63], v[232:235], v[244:247], v[48:63]
	v_mfma_f32_32x32x16_bf16 v[16:31], v[236:239], v[244:247], v[16:31]
	s_nop 15
	s_nop 7

	s_setprio 0
	s_branch .LBB0_338

.LBB0_484:
	s_andn2_saveexec_b64 s[48:49], s[48:49]
	s_cbranch_execz .LBB0_486
	s_and_b32 s50, s72, 0x10000
	v_add_u32_e32 v0, s50, v192
	v_or_b32_e32 v2, s50, v193
	v_add_u32_e32 v14, v0, v194
	v_add_u32_e32 v15, v0, v195
	v_add_u32_e32 v199, v0, v196
	v_add_u32_e32 v0, v0, v197
	v_add_u32_e32 v205, v2, v194
	v_add_u32_e32 v228, v2, v195
	v_add_u32_e32 v250, v2, v196
	v_add_u32_e32 v251, v2, v197
	s_setprio 1
	ds_read_b128 v[2:5], v14 offset:0
	ds_read_b128 v[6:9], v14 offset:4096
	ds_read_b128 v[10:13], v14 offset:8192
	ds_read_b128 v[214:217], v14 offset:12288
	ds_read_b128 v[246:249], v205 offset:0
	ds_read_b128 v[208:211], v205 offset:4096
	ds_read_b128 v[230:233], v15 offset:0
	ds_read_b128 v[234:237], v15 offset:4096
	ds_read_b128 v[238:241], v15 offset:8192
	ds_read_b128 v[242:245], v15 offset:12288
	s_waitcnt lgkmcnt(4)
	v_mfma_f32_32x32x16_bf16 v[128:143], v[2:5], v[246:249], v[128:143]
	v_mfma_f32_32x32x16_bf16 v[96:111], v[6:9], v[246:249], v[96:111]
	v_mfma_f32_32x32x16_bf16 v[64:79], v[10:13], v[246:249], v[64:79]
	v_mfma_f32_32x32x16_bf16 v[32:47], v[214:217], v[246:249], v[32:47]
	ds_read_b128 v[246:249], v228 offset:0
	v_mfma_f32_32x32x16_bf16 v[112:127], v[2:5], v[208:211], v[112:127]
	v_mfma_f32_32x32x16_bf16 v[80:95], v[6:9], v[208:211], v[80:95]
	v_mfma_f32_32x32x16_bf16 v[48:63], v[10:13], v[208:211], v[48:63]
	v_mfma_f32_32x32x16_bf16 v[16:31], v[214:217], v[208:211], v[16:31]
	ds_read_b128 v[208:211], v228 offset:4096
	ds_read_b128 v[2:5], v199 offset:0
	ds_read_b128 v[6:9], v199 offset:4096
	ds_read_b128 v[10:13], v199 offset:8192
	ds_read_b128 v[214:217], v199 offset:12288
	s_waitcnt lgkmcnt(5)
	v_mfma_f32_32x32x16_bf16 v[128:143], v[230:233], v[246:249], v[128:143]
	v_mfma_f32_32x32x16_bf16 v[96:111], v[234:237], v[246:249], v[96:111]
	v_mfma_f32_32x32x16_bf16 v[64:79], v[238:241], v[246:249], v[64:79]
	v_mfma_f32_32x32x16_bf16 v[32:47], v[242:245], v[246:249], v[32:47]
	ds_read_b128 v[246:249], v250 offset:0
	s_waitcnt lgkmcnt(5)
	v_mfma_f32_32x32x16_bf16 v[112:127], v[230:233], v[208:211], v[112:127]
	v_mfma_f32_32x32x16_bf16 v[80:95], v[234:237], v[208:211], v[80:95]
	v_mfma_f32_32x32x16_bf16 v[48:63], v[238:241], v[208:211], v[48:63]
	v_mfma_f32_32x32x16_bf16 v[16:31], v[242:245], v[208:211], v[16:31]
	ds_read_b128 v[208:211], v250 offset:4096
	ds_read_b128 v[230:233], v0 offset:0
	ds_read_b128 v[234:237], v0 offset:4096
	ds_read_b128 v[238:241], v0 offset:8192
	ds_read_b128 v[242:245], v0 offset:12288
	s_waitcnt lgkmcnt(5)
	v_mfma_f32_32x32x16_bf16 v[128:143], v[2:5], v[246:249], v[128:143]
	v_mfma_f32_32x32x16_bf16 v[96:111], v[6:9], v[246:249], v[96:111]
	v_mfma_f32_32x32x16_bf16 v[64:79], v[10:13], v[246:249], v[64:79]
	v_mfma_f32_32x32x16_bf16 v[32:47], v[214:217], v[246:249], v[32:47]
	ds_read_b128 v[246:249], v251 offset:0
	s_waitcnt lgkmcnt(5)
	v_mfma_f32_32x32x16_bf16 v[112:127], v[2:5], v[208:211], v[112:127]
	v_mfma_f32_32x32x16_bf16 v[80:95], v[6:9], v[208:211], v[80:95]
	v_mfma_f32_32x32x16_bf16 v[48:63], v[10:13], v[208:211], v[48:63]
	v_mfma_f32_32x32x16_bf16 v[16:31], v[214:217], v[208:211], v[16:31]
	ds_read_b128 v[208:211], v251 offset:4096
	s_waitcnt lgkmcnt(1)
	v_mfma_f32_32x32x16_bf16 v[128:143], v[230:233], v[246:249], v[128:143]
	v_mfma_f32_32x32x16_bf16 v[96:111], v[234:237], v[246:249], v[96:111]
	v_mfma_f32_32x32x16_bf16 v[64:79], v[238:241], v[246:249], v[64:79]
	v_mfma_f32_32x32x16_bf16 v[32:47], v[242:245], v[246:249], v[32:47]
	s_waitcnt lgkmcnt(0)
	v_mfma_f32_32x32x16_bf16 v[112:127], v[230:233], v[208:211], v[112:127]
	v_mfma_f32_32x32x16_bf16 v[80:95], v[234:237], v[208:211], v[80:95]
	v_mfma_f32_32x32x16_bf16 v[48:63], v[238:241], v[208:211], v[48:63]
	v_mfma_f32_32x32x16_bf16 v[16:31], v[242:245], v[208:211], v[16:31]
	s_nop 15
	s_nop 7

	s_setprio 0

.LBB0_491:
	s_andn2_saveexec_b64 s[48:49], s[48:49]
	s_cbranch_execz .LBB0_478
	s_and_b32 s50, s72, 0x10000
	v_add_u32_e32 v0, s50, v192
	v_or_b32_e32 v2, s50, v193
	v_add_u32_e32 v14, v0, v194
	v_add_u32_e32 v15, v0, v195
	v_add_u32_e32 v199, v0, v196
	v_add_u32_e32 v0, v0, v197
	v_add_u32_e32 v205, v2, v194
	v_add_u32_e32 v228, v2, v195
	v_add_u32_e32 v250, v2, v196
	v_add_u32_e32 v251, v2, v197
	s_setprio 1
	ds_read_b128 v[2:5], v14 offset:0
	ds_read_b128 v[6:9], v14 offset:4096
	ds_read_b128 v[10:13], v14 offset:8192
	ds_read_b128 v[208:211], v14 offset:12288
	ds_read_b128 v[242:245], v205 offset:0
	ds_read_b128 v[246:249], v205 offset:4096
	ds_read_b128 v[214:217], v15 offset:0
	ds_read_b128 v[230:233], v15 offset:4096
	ds_read_b128 v[234:237], v15 offset:8192
	ds_read_b128 v[238:241], v15 offset:12288
	s_waitcnt lgkmcnt(4)
	v_mfma_f32_32x32x16_bf16 v[128:143], v[2:5], v[242:245], v[128:143]
	v_mfma_f32_32x32x16_bf16 v[96:111], v[6:9], v[242:245], v[96:111]
	v_mfma_f32_32x32x16_bf16 v[64:79], v[10:13], v[242:245], v[64:79]
	v_mfma_f32_32x32x16_bf16 v[32:47], v[208:211], v[242:245], v[32:47]
	ds_read_b128 v[242:245], v228 offset:0
	v_mfma_f32_32x32x16_bf16 v[112:127], v[2:5], v[246:249], v[112:127]
	v_mfma_f32_32x32x16_bf16 v[80:95], v[6:9], v[246:249], v[80:95]
	v_mfma_f32_32x32x16_bf16 v[48:63], v[10:13], v[246:249], v[48:63]
	v_mfma_f32_32x32x16_bf16 v[16:31], v[208:211], v[246:249], v[16:31]
	ds_read_b128 v[246:249], v228 offset:4096
	ds_read_b128 v[2:5], v199 offset:0
	ds_read_b128 v[6:9], v199 offset:4096
	ds_read_b128 v[10:13], v199 offset:8192
	ds_read_b128 v[208:211], v199 offset:12288
	s_waitcnt lgkmcnt(5)
	v_mfma_f32_32x32x16_bf16 v[128:143], v[214:217], v[242:245], v[128:143]
	v_mfma_f32_32x32x16_bf16 v[96:111], v[230:233], v[242:245], v[96:111]
	v_mfma_f32_32x32x16_bf16 v[64:79], v[234:237], v[242:245], v[64:79]
	v_mfma_f32_32x32x16_bf16 v[32:47], v[238:241], v[242:245], v[32:47]
	ds_read_b128 v[242:245], v250 offset:0
	s_waitcnt lgkmcnt(5)
	v_mfma_f32_32x32x16_bf16 v[112:127], v[214:217], v[246:249], v[112:127]
	v_mfma_f32_32x32x16_bf16 v[80:95], v[230:233], v[246:249], v[80:95]
	v_mfma_f32_32x32x16_bf16 v[48:63], v[234:237], v[246:249], v[48:63]
	v_mfma_f32_32x32x16_bf16 v[16:31], v[238:241], v[246:249], v[16:31]
	ds_read_b128 v[246:249], v250 offset:4096
	ds_read_b128 v[214:217], v0 offset:0
	ds_read_b128 v[230:233], v0 offset:4096
	ds_read_b128 v[234:237], v0 offset:8192
	ds_read_b128 v[238:241], v0 offset:12288
	s_waitcnt lgkmcnt(5)
	v_mfma_f32_32x32x16_bf16 v[128:143], v[2:5], v[242:245], v[128:143]
	v_mfma_f32_32x32x16_bf16 v[96:111], v[6:9], v[242:245], v[96:111]
	v_mfma_f32_32x32x16_bf16 v[64:79], v[10:13], v[242:245], v[64:79]
	v_mfma_f32_32x32x16_bf16 v[32:47], v[208:211], v[242:245], v[32:47]
	ds_read_b128 v[242:245], v251 offset:0
	s_waitcnt lgkmcnt(5)
	v_mfma_f32_32x32x16_bf16 v[112:127], v[2:5], v[246:249], v[112:127]
	v_mfma_f32_32x32x16_bf16 v[80:95], v[6:9], v[246:249], v[80:95]
	v_mfma_f32_32x32x16_bf16 v[48:63], v[10:13], v[246:249], v[48:63]
	v_mfma_f32_32x32x16_bf16 v[16:31], v[208:211], v[246:249], v[16:31]
	ds_read_b128 v[246:249], v251 offset:4096
	s_waitcnt lgkmcnt(1)
	v_mfma_f32_32x32x16_bf16 v[128:143], v[214:217], v[242:245], v[128:143]
	v_mfma_f32_32x32x16_bf16 v[96:111], v[230:233], v[242:245], v[96:111]
	v_mfma_f32_32x32x16_bf16 v[64:79], v[234:237], v[242:245], v[64:79]
	v_mfma_f32_32x32x16_bf16 v[32:47], v[238:241], v[242:245], v[32:47]
	s_waitcnt lgkmcnt(0)
	v_mfma_f32_32x32x16_bf16 v[112:127], v[214:217], v[246:249], v[112:127]
	v_mfma_f32_32x32x16_bf16 v[80:95], v[230:233], v[246:249], v[80:95]
	v_mfma_f32_32x32x16_bf16 v[48:63], v[234:237], v[246:249], v[48:63]
	v_mfma_f32_32x32x16_bf16 v[16:31], v[238:241], v[246:249], v[16:31]
	s_nop 15
	s_nop 7

	s_setprio 0
	s_branch .LBB0_478

.LBB0_581:
	s_andn2_saveexec_b64 s[30:31], s[30:31]
	s_cbranch_execz .LBB0_583
	s_and_b32 s46, s27, 0x10000
	v_add_u32_e32 v0, s46, v195
	v_or_b32_e32 v2, s46, v196
	v_add_u32_e32 v14, v0, v197
	v_add_u32_e32 v15, v0, v198
	v_add_u32_e32 v208, v0, v199
	v_add_u32_e32 v0, v0, v200
	v_add_u32_e32 v209, v2, v197
	v_add_u32_e32 v210, v2, v198
	v_add_u32_e32 v211, v2, v199
	v_add_u32_e32 v214, v2, v200
	s_setprio 1
	ds_read_b128 v[2:5], v14 offset:0
	ds_read_b128 v[6:9], v14 offset:4096
	ds_read_b128 v[10:13], v14 offset:8192
	ds_read_b128 v[202:205], v14 offset:12288
	ds_read_b128 v[244:247], v209 offset:0
	ds_read_b128 v[248:251], v209 offset:4096
	ds_read_b128 v[228:231], v15 offset:0
	ds_read_b128 v[232:235], v15 offset:4096
	ds_read_b128 v[236:239], v15 offset:8192
	ds_read_b128 v[240:243], v15 offset:12288
	s_waitcnt lgkmcnt(4)
	v_mfma_f32_32x32x16_bf16 v[128:143], v[2:5], v[244:247], v[128:143]
	v_mfma_f32_32x32x16_bf16 v[96:111], v[6:9], v[244:247], v[96:111]
	v_mfma_f32_32x32x16_bf16 v[64:79], v[10:13], v[244:247], v[64:79]
	v_mfma_f32_32x32x16_bf16 v[32:47], v[202:205], v[244:247], v[32:47]
	ds_read_b128 v[244:247], v210 offset:0
	v_mfma_f32_32x32x16_bf16 v[112:127], v[2:5], v[248:251], v[112:127]
	v_mfma_f32_32x32x16_bf16 v[80:95], v[6:9], v[248:251], v[80:95]
	v_mfma_f32_32x32x16_bf16 v[48:63], v[10:13], v[248:251], v[48:63]
	v_mfma_f32_32x32x16_bf16 v[16:31], v[202:205], v[248:251], v[16:31]
	ds_read_b128 v[248:251], v210 offset:4096
	ds_read_b128 v[2:5], v208 offset:0
	ds_read_b128 v[6:9], v208 offset:4096
	ds_read_b128 v[10:13], v208 offset:8192
	ds_read_b128 v[202:205], v208 offset:12288
	s_waitcnt lgkmcnt(5)
	v_mfma_f32_32x32x16_bf16 v[128:143], v[228:231], v[244:247], v[128:143]
	v_mfma_f32_32x32x16_bf16 v[96:111], v[232:235], v[244:247], v[96:111]
	v_mfma_f32_32x32x16_bf16 v[64:79], v[236:239], v[244:247], v[64:79]
	v_mfma_f32_32x32x16_bf16 v[32:47], v[240:243], v[244:247], v[32:47]
	ds_read_b128 v[244:247], v211 offset:0
	s_waitcnt lgkmcnt(5)
	v_mfma_f32_32x32x16_bf16 v[112:127], v[228:231], v[248:251], v[112:127]
	v_mfma_f32_32x32x16_bf16 v[80:95], v[232:235], v[248:251], v[80:95]
	v_mfma_f32_32x32x16_bf16 v[48:63], v[236:239], v[248:251], v[48:63]
	v_mfma_f32_32x32x16_bf16 v[16:31], v[240:243], v[248:251], v[16:31]
	ds_read_b128 v[248:251], v211 offset:4096
	ds_read_b128 v[228:231], v0 offset:0
	ds_read_b128 v[232:235], v0 offset:4096
	ds_read_b128 v[236:239], v0 offset:8192
	ds_read_b128 v[240:243], v0 offset:12288
	s_waitcnt lgkmcnt(5)
	v_mfma_f32_32x32x16_bf16 v[128:143], v[2:5], v[244:247], v[128:143]
	v_mfma_f32_32x32x16_bf16 v[96:111], v[6:9], v[244:247], v[96:111]
	v_mfma_f32_32x32x16_bf16 v[64:79], v[10:13], v[244:247], v[64:79]
	v_mfma_f32_32x32x16_bf16 v[32:47], v[202:205], v[244:247], v[32:47]
	ds_read_b128 v[244:247], v214 offset:0
	s_waitcnt lgkmcnt(5)
	v_mfma_f32_32x32x16_bf16 v[112:127], v[2:5], v[248:251], v[112:127]
	v_mfma_f32_32x32x16_bf16 v[80:95], v[6:9], v[248:251], v[80:95]
	v_mfma_f32_32x32x16_bf16 v[48:63], v[10:13], v[248:251], v[48:63]
	v_mfma_f32_32x32x16_bf16 v[16:31], v[202:205], v[248:251], v[16:31]
	ds_read_b128 v[248:251], v214 offset:4096
	s_waitcnt lgkmcnt(1)
	v_mfma_f32_32x32x16_bf16 v[128:143], v[228:231], v[244:247], v[128:143]
	v_mfma_f32_32x32x16_bf16 v[96:111], v[232:235], v[244:247], v[96:111]
	v_mfma_f32_32x32x16_bf16 v[64:79], v[236:239], v[244:247], v[64:79]
	v_mfma_f32_32x32x16_bf16 v[32:47], v[240:243], v[244:247], v[32:47]
	s_waitcnt lgkmcnt(0)
	v_mfma_f32_32x32x16_bf16 v[112:127], v[228:231], v[248:251], v[112:127]
	v_mfma_f32_32x32x16_bf16 v[80:95], v[232:235], v[248:251], v[80:95]
	v_mfma_f32_32x32x16_bf16 v[48:63], v[236:239], v[248:251], v[48:63]
	v_mfma_f32_32x32x16_bf16 v[16:31], v[240:243], v[248:251], v[16:31]
	s_nop 15
	s_nop 7

	s_setprio 0

.LBB0_588:
	s_andn2_saveexec_b64 s[30:31], s[30:31]
	s_cbranch_execz .LBB0_575
	s_and_b32 s46, s27, 0x10000
	v_add_u32_e32 v0, s46, v195
	v_or_b32_e32 v2, s46, v196
	v_add_u32_e32 v14, v0, v197
	v_add_u32_e32 v15, v0, v198
	v_add_u32_e32 v208, v0, v199
	v_add_u32_e32 v0, v0, v200
	v_add_u32_e32 v209, v2, v197
	v_add_u32_e32 v210, v2, v198
	v_add_u32_e32 v211, v2, v199
	v_add_u32_e32 v214, v2, v200
	s_setprio 1
	ds_read_b128 v[2:5], v14 offset:0
	ds_read_b128 v[6:9], v14 offset:4096
	ds_read_b128 v[10:13], v14 offset:8192
	ds_read_b128 v[202:205], v14 offset:12288
	ds_read_b128 v[244:247], v209 offset:0
	ds_read_b128 v[248:251], v209 offset:4096
	ds_read_b128 v[228:231], v15 offset:0
	ds_read_b128 v[232:235], v15 offset:4096
	ds_read_b128 v[236:239], v15 offset:8192
	ds_read_b128 v[240:243], v15 offset:12288
	s_waitcnt lgkmcnt(4)
	v_mfma_f32_32x32x16_bf16 v[128:143], v[2:5], v[244:247], v[128:143]
	v_mfma_f32_32x32x16_bf16 v[96:111], v[6:9], v[244:247], v[96:111]
	v_mfma_f32_32x32x16_bf16 v[64:79], v[10:13], v[244:247], v[64:79]
	v_mfma_f32_32x32x16_bf16 v[32:47], v[202:205], v[244:247], v[32:47]
	ds_read_b128 v[244:247], v210 offset:0
	v_mfma_f32_32x32x16_bf16 v[112:127], v[2:5], v[248:251], v[112:127]
	v_mfma_f32_32x32x16_bf16 v[80:95], v[6:9], v[248:251], v[80:95]
	v_mfma_f32_32x32x16_bf16 v[48:63], v[10:13], v[248:251], v[48:63]
	v_mfma_f32_32x32x16_bf16 v[16:31], v[202:205], v[248:251], v[16:31]
	ds_read_b128 v[248:251], v210 offset:4096
	ds_read_b128 v[2:5], v208 offset:0
	ds_read_b128 v[6:9], v208 offset:4096
	ds_read_b128 v[10:13], v208 offset:8192
	ds_read_b128 v[202:205], v208 offset:12288
	s_waitcnt lgkmcnt(5)
	v_mfma_f32_32x32x16_bf16 v[128:143], v[228:231], v[244:247], v[128:143]
	v_mfma_f32_32x32x16_bf16 v[96:111], v[232:235], v[244:247], v[96:111]
	v_mfma_f32_32x32x16_bf16 v[64:79], v[236:239], v[244:247], v[64:79]
	v_mfma_f32_32x32x16_bf16 v[32:47], v[240:243], v[244:247], v[32:47]
	ds_read_b128 v[244:247], v211 offset:0
	s_waitcnt lgkmcnt(5)
	v_mfma_f32_32x32x16_bf16 v[112:127], v[228:231], v[248:251], v[112:127]
	v_mfma_f32_32x32x16_bf16 v[80:95], v[232:235], v[248:251], v[80:95]
	v_mfma_f32_32x32x16_bf16 v[48:63], v[236:239], v[248:251], v[48:63]
	v_mfma_f32_32x32x16_bf16 v[16:31], v[240:243], v[248:251], v[16:31]
	ds_read_b128 v[248:251], v211 offset:4096
	ds_read_b128 v[228:231], v0 offset:0
	ds_read_b128 v[232:235], v0 offset:4096
	ds_read_b128 v[236:239], v0 offset:8192
	ds_read_b128 v[240:243], v0 offset:12288
	s_waitcnt lgkmcnt(5)
	v_mfma_f32_32x32x16_bf16 v[128:143], v[2:5], v[244:247], v[128:143]
	v_mfma_f32_32x32x16_bf16 v[96:111], v[6:9], v[244:247], v[96:111]
	v_mfma_f32_32x32x16_bf16 v[64:79], v[10:13], v[244:247], v[64:79]
	v_mfma_f32_32x32x16_bf16 v[32:47], v[202:205], v[244:247], v[32:47]
	ds_read_b128 v[244:247], v214 offset:0
	s_waitcnt lgkmcnt(5)
	v_mfma_f32_32x32x16_bf16 v[112:127], v[2:5], v[248:251], v[112:127]
	v_mfma_f32_32x32x16_bf16 v[80:95], v[6:9], v[248:251], v[80:95]
	v_mfma_f32_32x32x16_bf16 v[48:63], v[10:13], v[248:251], v[48:63]
	v_mfma_f32_32x32x16_bf16 v[16:31], v[202:205], v[248:251], v[16:31]
	ds_read_b128 v[248:251], v214 offset:4096
	s_waitcnt lgkmcnt(1)
	v_mfma_f32_32x32x16_bf16 v[128:143], v[228:231], v[244:247], v[128:143]
	v_mfma_f32_32x32x16_bf16 v[96:111], v[232:235], v[244:247], v[96:111]
	v_mfma_f32_32x32x16_bf16 v[64:79], v[236:239], v[244:247], v[64:79]
	v_mfma_f32_32x32x16_bf16 v[32:47], v[240:243], v[244:247], v[32:47]
	s_waitcnt lgkmcnt(0)
	v_mfma_f32_32x32x16_bf16 v[112:127], v[228:231], v[248:251], v[112:127]
	v_mfma_f32_32x32x16_bf16 v[80:95], v[232:235], v[248:251], v[80:95]
	v_mfma_f32_32x32x16_bf16 v[48:63], v[236:239], v[248:251], v[48:63]
	v_mfma_f32_32x32x16_bf16 v[16:31], v[240:243], v[248:251], v[16:31]
	s_nop 15
	s_nop 7

	s_setprio 0
	s_branch .LBB0_575

.LBB0_603:
	s_andn2_saveexec_b64 s[22:23], s[22:23]
	s_cbranch_execz .LBB0_605
	s_and_b32 s56, s53, 0x10000
	v_add_u32_e32 v0, s56, v195
	v_or_b32_e32 v2, s56, v196
	v_add_u32_e32 v14, v0, v197
	v_add_u32_e32 v15, v0, v198
	v_add_u32_e32 v203, v0, v199
	v_add_u32_e32 v0, v0, v200
	v_add_u32_e32 v204, v2, v197
	v_add_u32_e32 v205, v2, v198
	v_add_u32_e32 v208, v2, v199
	v_add_u32_e32 v209, v2, v200
	s_setprio 1
	ds_read_b128 v[2:5], v14 offset:0
	ds_read_b128 v[6:9], v14 offset:4096
	ds_read_b128 v[10:13], v14 offset:8192
	ds_read_b128 v[228:231], v14 offset:12288
	ds_read_b128 v[248:251], v204 offset:0
	ds_read_b128 v[214:217], v204 offset:4096
	ds_read_b128 v[232:235], v15 offset:0
	ds_read_b128 v[236:239], v15 offset:4096
	ds_read_b128 v[240:243], v15 offset:8192
	ds_read_b128 v[244:247], v15 offset:12288
	s_waitcnt lgkmcnt(4)
	v_mfma_f32_32x32x16_bf16 v[128:143], v[2:5], v[248:251], v[128:143]
	v_mfma_f32_32x32x16_bf16 v[96:111], v[6:9], v[248:251], v[96:111]
	v_mfma_f32_32x32x16_bf16 v[64:79], v[10:13], v[248:251], v[64:79]
	v_mfma_f32_32x32x16_bf16 v[32:47], v[228:231], v[248:251], v[32:47]
	ds_read_b128 v[248:251], v205 offset:0
	v_mfma_f32_32x32x16_bf16 v[112:127], v[2:5], v[214:217], v[112:127]
	v_mfma_f32_32x32x16_bf16 v[80:95], v[6:9], v[214:217], v[80:95]
	v_mfma_f32_32x32x16_bf16 v[48:63], v[10:13], v[214:217], v[48:63]
	v_mfma_f32_32x32x16_bf16 v[16:31], v[228:231], v[214:217], v[16:31]
	ds_read_b128 v[214:217], v205 offset:4096
	ds_read_b128 v[2:5], v203 offset:0
	ds_read_b128 v[6:9], v203 offset:4096
	ds_read_b128 v[10:13], v203 offset:8192
	ds_read_b128 v[228:231], v203 offset:12288
	s_waitcnt lgkmcnt(5)
	v_mfma_f32_32x32x16_bf16 v[128:143], v[232:235], v[248:251], v[128:143]
	v_mfma_f32_32x32x16_bf16 v[96:111], v[236:239], v[248:251], v[96:111]
	v_mfma_f32_32x32x16_bf16 v[64:79], v[240:243], v[248:251], v[64:79]
	v_mfma_f32_32x32x16_bf16 v[32:47], v[244:247], v[248:251], v[32:47]
	ds_read_b128 v[248:251], v208 offset:0
	s_waitcnt lgkmcnt(5)
	v_mfma_f32_32x32x16_bf16 v[112:127], v[232:235], v[214:217], v[112:127]
	v_mfma_f32_32x32x16_bf16 v[80:95], v[236:239], v[214:217], v[80:95]
	v_mfma_f32_32x32x16_bf16 v[48:63], v[240:243], v[214:217], v[48:63]
	v_mfma_f32_32x32x16_bf16 v[16:31], v[244:247], v[214:217], v[16:31]
	ds_read_b128 v[214:217], v208 offset:4096
	ds_read_b128 v[232:235], v0 offset:0
	ds_read_b128 v[236:239], v0 offset:4096
	ds_read_b128 v[240:243], v0 offset:8192
	ds_read_b128 v[244:247], v0 offset:12288
	s_waitcnt lgkmcnt(5)
	v_mfma_f32_32x32x16_bf16 v[128:143], v[2:5], v[248:251], v[128:143]
	v_mfma_f32_32x32x16_bf16 v[96:111], v[6:9], v[248:251], v[96:111]
	v_mfma_f32_32x32x16_bf16 v[64:79], v[10:13], v[248:251], v[64:79]
	v_mfma_f32_32x32x16_bf16 v[32:47], v[228:231], v[248:251], v[32:47]
	ds_read_b128 v[248:251], v209 offset:0
	s_waitcnt lgkmcnt(5)
	v_mfma_f32_32x32x16_bf16 v[112:127], v[2:5], v[214:217], v[112:127]
	v_mfma_f32_32x32x16_bf16 v[80:95], v[6:9], v[214:217], v[80:95]
	v_mfma_f32_32x32x16_bf16 v[48:63], v[10:13], v[214:217], v[48:63]
	v_mfma_f32_32x32x16_bf16 v[16:31], v[228:231], v[214:217], v[16:31]
	ds_read_b128 v[214:217], v209 offset:4096
	s_waitcnt lgkmcnt(1)
	v_mfma_f32_32x32x16_bf16 v[128:143], v[232:235], v[248:251], v[128:143]
	v_mfma_f32_32x32x16_bf16 v[96:111], v[236:239], v[248:251], v[96:111]
	v_mfma_f32_32x32x16_bf16 v[64:79], v[240:243], v[248:251], v[64:79]
	v_mfma_f32_32x32x16_bf16 v[32:47], v[244:247], v[248:251], v[32:47]
	s_waitcnt lgkmcnt(0)
	v_mfma_f32_32x32x16_bf16 v[112:127], v[232:235], v[214:217], v[112:127]
	v_mfma_f32_32x32x16_bf16 v[80:95], v[236:239], v[214:217], v[80:95]
	v_mfma_f32_32x32x16_bf16 v[48:63], v[240:243], v[214:217], v[48:63]
	v_mfma_f32_32x32x16_bf16 v[16:31], v[244:247], v[214:217], v[16:31]
	s_nop 15
	s_nop 7

	s_setprio 0

.LBB0_611:
	s_andn2_saveexec_b64 s[22:23], s[22:23]
	s_cbranch_execz .LBB0_597
	s_and_b32 s56, s53, 0x10000
	v_add_u32_e32 v0, s56, v195
	v_or_b32_e32 v2, s56, v196
	v_add_u32_e32 v14, v0, v197
	v_add_u32_e32 v15, v0, v198
	v_add_u32_e32 v203, v0, v199
	v_add_u32_e32 v0, v0, v200
	v_add_u32_e32 v204, v2, v197
	v_add_u32_e32 v205, v2, v198
	v_add_u32_e32 v208, v2, v199
	v_add_u32_e32 v209, v2, v200
	s_setprio 1
	ds_read_b128 v[2:5], v14 offset:0
	ds_read_b128 v[6:9], v14 offset:4096
	ds_read_b128 v[10:13], v14 offset:8192
	ds_read_b128 v[214:217], v14 offset:12288
	ds_read_b128 v[244:247], v204 offset:0
	ds_read_b128 v[248:251], v204 offset:4096
	ds_read_b128 v[228:231], v15 offset:0
	ds_read_b128 v[232:235], v15 offset:4096
	ds_read_b128 v[236:239], v15 offset:8192
	ds_read_b128 v[240:243], v15 offset:12288
	s_waitcnt lgkmcnt(4)
	v_mfma_f32_32x32x16_bf16 v[128:143], v[2:5], v[244:247], v[128:143]
	v_mfma_f32_32x32x16_bf16 v[96:111], v[6:9], v[244:247], v[96:111]
	v_mfma_f32_32x32x16_bf16 v[64:79], v[10:13], v[244:247], v[64:79]
	v_mfma_f32_32x32x16_bf16 v[32:47], v[214:217], v[244:247], v[32:47]
	ds_read_b128 v[244:247], v205 offset:0
	v_mfma_f32_32x32x16_bf16 v[112:127], v[2:5], v[248:251], v[112:127]
	v_mfma_f32_32x32x16_bf16 v[80:95], v[6:9], v[248:251], v[80:95]
	v_mfma_f32_32x32x16_bf16 v[48:63], v[10:13], v[248:251], v[48:63]
	v_mfma_f32_32x32x16_bf16 v[16:31], v[214:217], v[248:251], v[16:31]
	ds_read_b128 v[248:251], v205 offset:4096
	ds_read_b128 v[2:5], v203 offset:0
	ds_read_b128 v[6:9], v203 offset:4096
	ds_read_b128 v[10:13], v203 offset:8192
	ds_read_b128 v[214:217], v203 offset:12288
	s_waitcnt lgkmcnt(5)
	v_mfma_f32_32x32x16_bf16 v[128:143], v[228:231], v[244:247], v[128:143]
	v_mfma_f32_32x32x16_bf16 v[96:111], v[232:235], v[244:247], v[96:111]
	v_mfma_f32_32x32x16_bf16 v[64:79], v[236:239], v[244:247], v[64:79]
	v_mfma_f32_32x32x16_bf16 v[32:47], v[240:243], v[244:247], v[32:47]
	ds_read_b128 v[244:247], v208 offset:0
	s_waitcnt lgkmcnt(5)
	v_mfma_f32_32x32x16_bf16 v[112:127], v[228:231], v[248:251], v[112:127]
	v_mfma_f32_32x32x16_bf16 v[80:95], v[232:235], v[248:251], v[80:95]
	v_mfma_f32_32x32x16_bf16 v[48:63], v[236:239], v[248:251], v[48:63]
	v_mfma_f32_32x32x16_bf16 v[16:31], v[240:243], v[248:251], v[16:31]
	ds_read_b128 v[248:251], v208 offset:4096
	ds_read_b128 v[228:231], v0 offset:0
	ds_read_b128 v[232:235], v0 offset:4096
	ds_read_b128 v[236:239], v0 offset:8192
	ds_read_b128 v[240:243], v0 offset:12288
	s_waitcnt lgkmcnt(5)
	v_mfma_f32_32x32x16_bf16 v[128:143], v[2:5], v[244:247], v[128:143]
	v_mfma_f32_32x32x16_bf16 v[96:111], v[6:9], v[244:247], v[96:111]
	v_mfma_f32_32x32x16_bf16 v[64:79], v[10:13], v[244:247], v[64:79]
	v_mfma_f32_32x32x16_bf16 v[32:47], v[214:217], v[244:247], v[32:47]
	ds_read_b128 v[244:247], v209 offset:0
	s_waitcnt lgkmcnt(5)
	v_mfma_f32_32x32x16_bf16 v[112:127], v[2:5], v[248:251], v[112:127]
	v_mfma_f32_32x32x16_bf16 v[80:95], v[6:9], v[248:251], v[80:95]
	v_mfma_f32_32x32x16_bf16 v[48:63], v[10:13], v[248:251], v[48:63]
	v_mfma_f32_32x32x16_bf16 v[16:31], v[214:217], v[248:251], v[16:31]
	ds_read_b128 v[248:251], v209 offset:4096
	s_waitcnt lgkmcnt(1)
	v_mfma_f32_32x32x16_bf16 v[128:143], v[228:231], v[244:247], v[128:143]
	v_mfma_f32_32x32x16_bf16 v[96:111], v[232:235], v[244:247], v[96:111]
	v_mfma_f32_32x32x16_bf16 v[64:79], v[236:239], v[244:247], v[64:79]
	v_mfma_f32_32x32x16_bf16 v[32:47], v[240:243], v[244:247], v[32:47]
	s_waitcnt lgkmcnt(0)
	v_mfma_f32_32x32x16_bf16 v[112:127], v[228:231], v[248:251], v[112:127]
	v_mfma_f32_32x32x16_bf16 v[80:95], v[232:235], v[248:251], v[80:95]
	v_mfma_f32_32x32x16_bf16 v[48:63], v[236:239], v[248:251], v[48:63]
	v_mfma_f32_32x32x16_bf16 v[16:31], v[240:243], v[248:251], v[16:31]
	s_nop 15
	s_nop 7

	s_setprio 0
	v_add_u32_e32 v202, 1, v202
	s_branch .LBB0_597

.LBB0_719:
	s_andn2_saveexec_b64 s[20:21], s[20:21]
	s_cbranch_execz .LBB0_721
	s_and_b32 s48, s26, 0x10000
	v_add_u32_e32 v0, s48, v195
	v_or_b32_e32 v2, s48, v196
	v_add_u32_e32 v14, v0, v197
	v_add_u32_e32 v15, v0, v198
	v_add_u32_e32 v208, v0, v199
	v_add_u32_e32 v0, v0, v200
	v_add_u32_e32 v209, v2, v197
	v_add_u32_e32 v210, v2, v198
	v_add_u32_e32 v211, v2, v199
	v_add_u32_e32 v214, v2, v200
	s_setprio 1
	ds_read_b128 v[2:5], v14 offset:0
	ds_read_b128 v[6:9], v14 offset:4096
	ds_read_b128 v[10:13], v14 offset:8192
	ds_read_b128 v[202:205], v14 offset:12288
	ds_read_b128 v[244:247], v209 offset:0
	ds_read_b128 v[248:251], v209 offset:4096
	ds_read_b128 v[228:231], v15 offset:0
	ds_read_b128 v[232:235], v15 offset:4096
	ds_read_b128 v[236:239], v15 offset:8192
	ds_read_b128 v[240:243], v15 offset:12288
	s_waitcnt lgkmcnt(4)
	v_mfma_f32_32x32x16_bf16 v[128:143], v[2:5], v[244:247], v[128:143]
	v_mfma_f32_32x32x16_bf16 v[96:111], v[6:9], v[244:247], v[96:111]
	v_mfma_f32_32x32x16_bf16 v[64:79], v[10:13], v[244:247], v[64:79]
	v_mfma_f32_32x32x16_bf16 v[32:47], v[202:205], v[244:247], v[32:47]
	ds_read_b128 v[244:247], v210 offset:0
	v_mfma_f32_32x32x16_bf16 v[112:127], v[2:5], v[248:251], v[112:127]
	v_mfma_f32_32x32x16_bf16 v[80:95], v[6:9], v[248:251], v[80:95]
	v_mfma_f32_32x32x16_bf16 v[48:63], v[10:13], v[248:251], v[48:63]
	v_mfma_f32_32x32x16_bf16 v[16:31], v[202:205], v[248:251], v[16:31]
	ds_read_b128 v[248:251], v210 offset:4096
	ds_read_b128 v[2:5], v208 offset:0
	ds_read_b128 v[6:9], v208 offset:4096
	ds_read_b128 v[10:13], v208 offset:8192
	ds_read_b128 v[202:205], v208 offset:12288
	s_waitcnt lgkmcnt(5)
	v_mfma_f32_32x32x16_bf16 v[128:143], v[228:231], v[244:247], v[128:143]
	v_mfma_f32_32x32x16_bf16 v[96:111], v[232:235], v[244:247], v[96:111]
	v_mfma_f32_32x32x16_bf16 v[64:79], v[236:239], v[244:247], v[64:79]
	v_mfma_f32_32x32x16_bf16 v[32:47], v[240:243], v[244:247], v[32:47]
	ds_read_b128 v[244:247], v211 offset:0
	s_waitcnt lgkmcnt(5)
	v_mfma_f32_32x32x16_bf16 v[112:127], v[228:231], v[248:251], v[112:127]
	v_mfma_f32_32x32x16_bf16 v[80:95], v[232:235], v[248:251], v[80:95]
	v_mfma_f32_32x32x16_bf16 v[48:63], v[236:239], v[248:251], v[48:63]
	v_mfma_f32_32x32x16_bf16 v[16:31], v[240:243], v[248:251], v[16:31]
	ds_read_b128 v[248:251], v211 offset:4096
	ds_read_b128 v[228:231], v0 offset:0
	ds_read_b128 v[232:235], v0 offset:4096
	ds_read_b128 v[236:239], v0 offset:8192
	ds_read_b128 v[240:243], v0 offset:12288
	s_waitcnt lgkmcnt(5)
	v_mfma_f32_32x32x16_bf16 v[128:143], v[2:5], v[244:247], v[128:143]
	v_mfma_f32_32x32x16_bf16 v[96:111], v[6:9], v[244:247], v[96:111]
	v_mfma_f32_32x32x16_bf16 v[64:79], v[10:13], v[244:247], v[64:79]
	v_mfma_f32_32x32x16_bf16 v[32:47], v[202:205], v[244:247], v[32:47]
	ds_read_b128 v[244:247], v214 offset:0
	s_waitcnt lgkmcnt(5)
	v_mfma_f32_32x32x16_bf16 v[112:127], v[2:5], v[248:251], v[112:127]
	v_mfma_f32_32x32x16_bf16 v[80:95], v[6:9], v[248:251], v[80:95]
	v_mfma_f32_32x32x16_bf16 v[48:63], v[10:13], v[248:251], v[48:63]
	v_mfma_f32_32x32x16_bf16 v[16:31], v[202:205], v[248:251], v[16:31]
	ds_read_b128 v[248:251], v214 offset:4096
	s_waitcnt lgkmcnt(1)
	v_mfma_f32_32x32x16_bf16 v[128:143], v[228:231], v[244:247], v[128:143]
	v_mfma_f32_32x32x16_bf16 v[96:111], v[232:235], v[244:247], v[96:111]
	v_mfma_f32_32x32x16_bf16 v[64:79], v[236:239], v[244:247], v[64:79]
	v_mfma_f32_32x32x16_bf16 v[32:47], v[240:243], v[244:247], v[32:47]
	s_waitcnt lgkmcnt(0)
	v_mfma_f32_32x32x16_bf16 v[112:127], v[228:231], v[248:251], v[112:127]
	v_mfma_f32_32x32x16_bf16 v[80:95], v[232:235], v[248:251], v[80:95]
	v_mfma_f32_32x32x16_bf16 v[48:63], v[236:239], v[248:251], v[48:63]
	v_mfma_f32_32x32x16_bf16 v[16:31], v[240:243], v[248:251], v[16:31]
	s_nop 15
	s_nop 7

	s_setprio 0

.LBB0_726:
	s_andn2_saveexec_b64 s[20:21], s[20:21]
	s_cbranch_execz .LBB0_713
	s_and_b32 s48, s26, 0x10000
	v_add_u32_e32 v0, s48, v195
	v_or_b32_e32 v2, s48, v196
	v_add_u32_e32 v14, v0, v197
	v_add_u32_e32 v15, v0, v198
	v_add_u32_e32 v208, v0, v199
	v_add_u32_e32 v0, v0, v200
	v_add_u32_e32 v209, v2, v197
	v_add_u32_e32 v210, v2, v198
	v_add_u32_e32 v211, v2, v199
	v_add_u32_e32 v214, v2, v200
	s_setprio 1
	ds_read_b128 v[2:5], v14 offset:0
	ds_read_b128 v[6:9], v14 offset:4096
	ds_read_b128 v[10:13], v14 offset:8192
	ds_read_b128 v[202:205], v14 offset:12288
	ds_read_b128 v[244:247], v209 offset:0
	ds_read_b128 v[248:251], v209 offset:4096
	ds_read_b128 v[228:231], v15 offset:0
	ds_read_b128 v[232:235], v15 offset:4096
	ds_read_b128 v[236:239], v15 offset:8192
	ds_read_b128 v[240:243], v15 offset:12288
	s_waitcnt lgkmcnt(4)
	v_mfma_f32_32x32x16_bf16 v[128:143], v[2:5], v[244:247], v[128:143]
	v_mfma_f32_32x32x16_bf16 v[96:111], v[6:9], v[244:247], v[96:111]
	v_mfma_f32_32x32x16_bf16 v[64:79], v[10:13], v[244:247], v[64:79]
	v_mfma_f32_32x32x16_bf16 v[32:47], v[202:205], v[244:247], v[32:47]
	ds_read_b128 v[244:247], v210 offset:0
	v_mfma_f32_32x32x16_bf16 v[112:127], v[2:5], v[248:251], v[112:127]
	v_mfma_f32_32x32x16_bf16 v[80:95], v[6:9], v[248:251], v[80:95]
	v_mfma_f32_32x32x16_bf16 v[48:63], v[10:13], v[248:251], v[48:63]
	v_mfma_f32_32x32x16_bf16 v[16:31], v[202:205], v[248:251], v[16:31]
	ds_read_b128 v[248:251], v210 offset:4096
	ds_read_b128 v[2:5], v208 offset:0
	ds_read_b128 v[6:9], v208 offset:4096
	ds_read_b128 v[10:13], v208 offset:8192
	ds_read_b128 v[202:205], v208 offset:12288
	s_waitcnt lgkmcnt(5)
	v_mfma_f32_32x32x16_bf16 v[128:143], v[228:231], v[244:247], v[128:143]
	v_mfma_f32_32x32x16_bf16 v[96:111], v[232:235], v[244:247], v[96:111]
	v_mfma_f32_32x32x16_bf16 v[64:79], v[236:239], v[244:247], v[64:79]
	v_mfma_f32_32x32x16_bf16 v[32:47], v[240:243], v[244:247], v[32:47]
	ds_read_b128 v[244:247], v211 offset:0
	s_waitcnt lgkmcnt(5)
	v_mfma_f32_32x32x16_bf16 v[112:127], v[228:231], v[248:251], v[112:127]
	v_mfma_f32_32x32x16_bf16 v[80:95], v[232:235], v[248:251], v[80:95]
	v_mfma_f32_32x32x16_bf16 v[48:63], v[236:239], v[248:251], v[48:63]
	v_mfma_f32_32x32x16_bf16 v[16:31], v[240:243], v[248:251], v[16:31]
	ds_read_b128 v[248:251], v211 offset:4096
	ds_read_b128 v[228:231], v0 offset:0
	ds_read_b128 v[232:235], v0 offset:4096
	ds_read_b128 v[236:239], v0 offset:8192
	ds_read_b128 v[240:243], v0 offset:12288
	s_waitcnt lgkmcnt(5)
	v_mfma_f32_32x32x16_bf16 v[128:143], v[2:5], v[244:247], v[128:143]
	v_mfma_f32_32x32x16_bf16 v[96:111], v[6:9], v[244:247], v[96:111]
	v_mfma_f32_32x32x16_bf16 v[64:79], v[10:13], v[244:247], v[64:79]
	v_mfma_f32_32x32x16_bf16 v[32:47], v[202:205], v[244:247], v[32:47]
	ds_read_b128 v[244:247], v214 offset:0
	s_waitcnt lgkmcnt(5)
	v_mfma_f32_32x32x16_bf16 v[112:127], v[2:5], v[248:251], v[112:127]
	v_mfma_f32_32x32x16_bf16 v[80:95], v[6:9], v[248:251], v[80:95]
	v_mfma_f32_32x32x16_bf16 v[48:63], v[10:13], v[248:251], v[48:63]
	v_mfma_f32_32x32x16_bf16 v[16:31], v[202:205], v[248:251], v[16:31]
	ds_read_b128 v[248:251], v214 offset:4096
	s_waitcnt lgkmcnt(1)
	v_mfma_f32_32x32x16_bf16 v[128:143], v[228:231], v[244:247], v[128:143]
	v_mfma_f32_32x32x16_bf16 v[96:111], v[232:235], v[244:247], v[96:111]
	v_mfma_f32_32x32x16_bf16 v[64:79], v[236:239], v[244:247], v[64:79]
	v_mfma_f32_32x32x16_bf16 v[32:47], v[240:243], v[244:247], v[32:47]
	s_waitcnt lgkmcnt(0)
	v_mfma_f32_32x32x16_bf16 v[112:127], v[228:231], v[248:251], v[112:127]
	v_mfma_f32_32x32x16_bf16 v[80:95], v[232:235], v[248:251], v[80:95]
	v_mfma_f32_32x32x16_bf16 v[48:63], v[236:239], v[248:251], v[48:63]
	v_mfma_f32_32x32x16_bf16 v[16:31], v[240:243], v[248:251], v[16:31]
	s_nop 15
	s_nop 7

	s_setprio 0
	s_branch .LBB0_713
